# leader pre-advances its clock by 8 units across its sweep boundary
# baseline (speedup 1.0000x reference)
.Lxp_noswe:
	s_mov_b32 s80, s81
	s_mov_b32 s81, s94
	s_add_i32 s25, s25, 1
	s_cmp_eq_u32 s82, 1
	s_cbranch_scc0 .Lxp_nojump
	s_add_i32 s2, s97, 17280
	s_and_b32 s2, s2, 0x3fff
	v_mov_b32_e32 v245, s2
	s_mov_b64 exec, 1
	global_store_dword v[246:247], v245, off
	s_mov_b64 exec, -1
